# plus: top-k bit loop exits early once every query's threshold set has exactly 15 members
# speedup vs baseline: 1.0063x; 1.0063x over previous
.Ltk_bit_loop:
	s_or_b32 s14, s14, s32
	s_or_b32 s15, s15, s32
	s_or_b32 s16, s16, s32
	s_or_b32 s17, s17, s32
	v_cmp_le_u32_e64 s[22:23], s14, v0
	v_cmp_le_u32_e64 s[24:25], s14, v8
	v_cmp_le_u32_e64 s[26:27], s15, v1
	v_cmp_le_u32_e64 s[28:29], s15, v9
	v_cmp_le_u32_e64 s[30:31], s16, v2
	v_cmp_le_u32_e64 vcc, s16, v10
	v_cmp_le_u32_e64 s[34:35], s17, v3
	v_cmp_le_u32_e64 s[38:39], s17, v11
	s_or_b32 s18, s18, s32
	s_or_b32 s19, s19, s32
	s_or_b32 s20, s20, s32
	s_or_b32 s21, s21, s32
	v_cmp_le_u32_e64 s[40:41], s18, v4
	v_cmp_le_u32_e64 s[42:43], s18, v12
	v_cmp_le_u32_e64 s[44:45], s19, v5
	v_cmp_le_u32_e64 s[46:47], s19, v13
	v_cmp_le_u32_e64 s[0:1], s20, v6
	v_cmp_le_u32_e64 s[2:3], s20, v14
	v_cmp_le_u32_e64 s[4:5], s21, v7
	v_cmp_le_u32_e64 s[10:11], s21, v15
	s_bcnt1_i32_b64 s48, s[22:23]
	s_bcnt1_i32_b64 s49, s[24:25]
	s_add_i32 s48, s48, s49
	s_cmp_gt_u32 s48, 14
	s_cselect_b32 s48, 0, s32
	s_xor_b32 s14, s14, s48
	s_bcnt1_i32_b64 s48, s[26:27]
	s_bcnt1_i32_b64 s49, s[28:29]
	s_add_i32 s48, s48, s49
	s_cmp_gt_u32 s48, 14
	s_cselect_b32 s48, 0, s32
	s_xor_b32 s15, s15, s48
	s_bcnt1_i32_b64 s48, s[30:31]
	s_bcnt1_i32_b64 s49, vcc
	s_add_i32 s48, s48, s49
	s_cmp_gt_u32 s48, 14
	s_cselect_b32 s48, 0, s32
	s_xor_b32 s16, s16, s48
	s_bcnt1_i32_b64 s48, s[34:35]
	s_bcnt1_i32_b64 s49, s[38:39]
	s_add_i32 s48, s48, s49
	s_cmp_gt_u32 s48, 14
	s_cselect_b32 s48, 0, s32
	s_xor_b32 s17, s17, s48
	s_bcnt1_i32_b64 s48, s[40:41]
	s_bcnt1_i32_b64 s49, s[42:43]
	s_add_i32 s48, s48, s49
	s_cmp_gt_u32 s48, 14
	s_cselect_b32 s48, 0, s32
	s_xor_b32 s18, s18, s48
	s_bcnt1_i32_b64 s48, s[44:45]
	s_bcnt1_i32_b64 s49, s[46:47]
	s_add_i32 s48, s48, s49
	s_cmp_gt_u32 s48, 14
	s_cselect_b32 s48, 0, s32
	s_xor_b32 s19, s19, s48
	s_bcnt1_i32_b64 s48, s[0:1]
	s_bcnt1_i32_b64 s49, s[2:3]
	s_add_i32 s48, s48, s49
	s_cmp_gt_u32 s48, 14
	s_cselect_b32 s48, 0, s32
	s_xor_b32 s20, s20, s48
	s_bcnt1_i32_b64 s48, s[4:5]
	s_bcnt1_i32_b64 s49, s[10:11]
	s_add_i32 s48, s48, s49
	s_cmp_gt_u32 s48, 14
	s_cselect_b32 s48, 0, s32
	s_xor_b32 s21, s21, s48
	s_and_b32 s48, s32, 0x11110
	s_cbranch_scc0 .Ltk_nocheck
	v_cmp_le_u32_e64 s[22:23], s14, v0
	v_cmp_le_u32_e64 s[24:25], s14, v8
	v_cmp_le_u32_e64 s[26:27], s15, v1
	v_cmp_le_u32_e64 s[28:29], s15, v9
	v_cmp_le_u32_e64 s[30:31], s16, v2
	v_cmp_le_u32_e64 vcc, s16, v10
	v_cmp_le_u32_e64 s[34:35], s17, v3
	v_cmp_le_u32_e64 s[38:39], s17, v11
	v_cmp_le_u32_e64 s[40:41], s18, v4
	v_cmp_le_u32_e64 s[42:43], s18, v12
	v_cmp_le_u32_e64 s[44:45], s19, v5
	v_cmp_le_u32_e64 s[46:47], s19, v13
	v_cmp_le_u32_e64 s[0:1], s20, v6
	v_cmp_le_u32_e64 s[2:3], s20, v14
	v_cmp_le_u32_e64 s[4:5], s21, v7
	v_cmp_le_u32_e64 s[10:11], s21, v15
	s_mov_b32 s49, 0
	s_bcnt1_i32_b64 s48, s[22:23]
	s_bcnt1_i32_b64 s22, s[24:25]
	s_add_i32 s48, s48, s22
	s_xor_b32 s48, s48, 15
	s_or_b32 s49, s49, s48
	s_bcnt1_i32_b64 s48, s[26:27]
	s_bcnt1_i32_b64 s26, s[28:29]
	s_add_i32 s48, s48, s26
	s_xor_b32 s48, s48, 15
	s_or_b32 s49, s49, s48
	s_bcnt1_i32_b64 s48, s[30:31]
	s_bcnt1_i32_b64 s30, vcc
	s_add_i32 s48, s48, s30
	s_xor_b32 s48, s48, 15
	s_or_b32 s49, s49, s48
	s_bcnt1_i32_b64 s48, s[34:35]
	s_bcnt1_i32_b64 s34, s[38:39]
	s_add_i32 s48, s48, s34
	s_xor_b32 s48, s48, 15
	s_or_b32 s49, s49, s48
	s_bcnt1_i32_b64 s48, s[40:41]
	s_bcnt1_i32_b64 s40, s[42:43]
	s_add_i32 s48, s48, s40
	s_xor_b32 s48, s48, 15
	s_or_b32 s49, s49, s48
	s_bcnt1_i32_b64 s48, s[44:45]
	s_bcnt1_i32_b64 s44, s[46:47]
	s_add_i32 s48, s48, s44
	s_xor_b32 s48, s48, 15
	s_or_b32 s49, s49, s48
	s_bcnt1_i32_b64 s48, s[0:1]
	s_bcnt1_i32_b64 s0, s[2:3]
	s_add_i32 s48, s48, s0
	s_xor_b32 s48, s48, 15
	s_or_b32 s49, s49, s48
	s_bcnt1_i32_b64 s48, s[4:5]
	s_bcnt1_i32_b64 s4, s[10:11]
	s_add_i32 s48, s48, s4
	s_xor_b32 s48, s48, 15
	s_or_b32 s49, s49, s48
	s_cmp_eq_u32 s49, 0
	s_cbranch_scc1 .Ltk_done
.Ltk_nocheck:
	s_lshr_b32 s32, s32, 1
	s_cbranch_scc1 .Ltk_bit_loop
.Ltk_done:
	v_cmp_gt_i32_e64 s[22:23], s80, v117
	v_cmp_gt_i32_e64 s[24:25], s80, v200
	v_cmp_eq_u32_e64 s[26:27], s80, v117
	v_cmp_eq_u32_e64 s[28:29], s80, v200
	v_cmp_lt_u32_e64 s[30:31], s14, v0
	v_cmp_lt_u32_e64 s[44:45], s14, v8
	v_cmp_eq_u32_e64 s[34:35], s14, v0
	v_cmp_eq_u32_e64 s[38:39], s14, v8
	s_bcnt1_i32_b64 s48, s[30:31]
	s_bcnt1_i32_b64 s49, s[44:45]
	s_add_i32 s48, s48, s49
	s_sub_i32 s48, 15, s48
	s_and_b64 s[34:35], s[34:35], s[22:23]
	s_and_b64 s[38:39], s[38:39], s[24:25]
	s_bcnt1_i32_b64 s49, s[34:35]
	v_and_b32_e32 v17, s34, v116
	v_and_b32_e32 v18, s35, v115
	v_bcnt_u32_b32 v17, v17, 0
	v_bcnt_u32_b32 v17, v18, v17
	v_and_b32_e32 v18, s38, v116
	v_and_b32_e32 v19, s39, v115
	v_bcnt_u32_b32 v18, v18, s49
	v_bcnt_u32_b32 v18, v19, v18
	v_cmp_gt_i32_e64 s[40:41], s48, v17
	v_cmp_gt_i32_e64 s[42:43], s48, v18
	s_and_b64 s[40:41], s[40:41], s[34:35]
	s_and_b64 s[42:43], s[42:43], s[38:39]
	s_or_b64 s[40:41], s[40:41], s[30:31]
	s_or_b64 s[42:43], s[42:43], s[44:45]
	s_or_b64 s[40:41], s[40:41], s[26:27]
	s_or_b64 s[42:43], s[42:43], s[28:29]
	v_mov_b32_e32 v32, s40
	v_mov_b32_e32 v33, s41
	v_mov_b32_e32 v34, s42
	v_mov_b32_e32 v35, s43
	v_cmp_lt_u32_e64 s[30:31], s15, v1
	v_cmp_lt_u32_e64 s[44:45], s15, v9
	v_cmp_eq_u32_e64 s[34:35], s15, v1
	v_cmp_eq_u32_e64 s[38:39], s15, v9
	s_bcnt1_i32_b64 s48, s[30:31]
	s_bcnt1_i32_b64 s49, s[44:45]
	s_add_i32 s48, s48, s49
	s_sub_i32 s48, 15, s48
	s_and_b64 s[34:35], s[34:35], s[22:23]
	s_and_b64 s[38:39], s[38:39], s[24:25]
	s_bcnt1_i32_b64 s49, s[34:35]
	v_and_b32_e32 v17, s34, v116
	v_and_b32_e32 v18, s35, v115
	v_bcnt_u32_b32 v17, v17, 0
	v_bcnt_u32_b32 v17, v18, v17
	v_and_b32_e32 v18, s38, v116
	v_and_b32_e32 v19, s39, v115
	v_bcnt_u32_b32 v18, v18, s49
	v_bcnt_u32_b32 v18, v19, v18
	v_cmp_gt_i32_e64 s[40:41], s48, v17
	v_cmp_gt_i32_e64 s[42:43], s48, v18
	s_and_b64 s[40:41], s[40:41], s[34:35]
	s_and_b64 s[42:43], s[42:43], s[38:39]
	s_or_b64 s[40:41], s[40:41], s[30:31]
	s_or_b64 s[42:43], s[42:43], s[44:45]
	s_or_b64 s[40:41], s[40:41], s[26:27]
	s_or_b64 s[42:43], s[42:43], s[28:29]
	v_mov_b32_e32 v36, s40
	v_mov_b32_e32 v37, s41
	v_mov_b32_e32 v38, s42
	v_mov_b32_e32 v39, s43
	v_cmp_lt_u32_e64 s[30:31], s16, v2
	v_cmp_lt_u32_e64 s[44:45], s16, v10
	v_cmp_eq_u32_e64 s[34:35], s16, v2
	v_cmp_eq_u32_e64 s[38:39], s16, v10
	s_bcnt1_i32_b64 s48, s[30:31]
	s_bcnt1_i32_b64 s49, s[44:45]
	s_add_i32 s48, s48, s49
	s_sub_i32 s48, 15, s48
	s_and_b64 s[34:35], s[34:35], s[22:23]
	s_and_b64 s[38:39], s[38:39], s[24:25]
	s_bcnt1_i32_b64 s49, s[34:35]
	v_and_b32_e32 v17, s34, v116
	v_and_b32_e32 v18, s35, v115
	v_bcnt_u32_b32 v17, v17, 0
	v_bcnt_u32_b32 v17, v18, v17
	v_and_b32_e32 v18, s38, v116
	v_and_b32_e32 v19, s39, v115
	v_bcnt_u32_b32 v18, v18, s49
	v_bcnt_u32_b32 v18, v19, v18
	v_cmp_gt_i32_e64 s[40:41], s48, v17
	v_cmp_gt_i32_e64 s[42:43], s48, v18
	s_and_b64 s[40:41], s[40:41], s[34:35]
	s_and_b64 s[42:43], s[42:43], s[38:39]
	s_or_b64 s[40:41], s[40:41], s[30:31]
	s_or_b64 s[42:43], s[42:43], s[44:45]
	s_or_b64 s[40:41], s[40:41], s[26:27]
	s_or_b64 s[42:43], s[42:43], s[28:29]
	v_mov_b32_e32 v40, s40
	v_mov_b32_e32 v41, s41
	v_mov_b32_e32 v42, s42
	v_mov_b32_e32 v43, s43
	v_cmp_lt_u32_e64 s[30:31], s17, v3
	v_cmp_lt_u32_e64 s[44:45], s17, v11
	v_cmp_eq_u32_e64 s[34:35], s17, v3
	v_cmp_eq_u32_e64 s[38:39], s17, v11
	s_bcnt1_i32_b64 s48, s[30:31]
	s_bcnt1_i32_b64 s49, s[44:45]
	s_add_i32 s48, s48, s49
	s_sub_i32 s48, 15, s48
	s_and_b64 s[34:35], s[34:35], s[22:23]
	s_and_b64 s[38:39], s[38:39], s[24:25]
	s_bcnt1_i32_b64 s49, s[34:35]
	v_and_b32_e32 v17, s34, v116
	v_and_b32_e32 v18, s35, v115
	v_bcnt_u32_b32 v17, v17, 0
	v_bcnt_u32_b32 v17, v18, v17
	v_and_b32_e32 v18, s38, v116
	v_and_b32_e32 v19, s39, v115
	v_bcnt_u32_b32 v18, v18, s49
	v_bcnt_u32_b32 v18, v19, v18
	v_cmp_gt_i32_e64 s[40:41], s48, v17
	v_cmp_gt_i32_e64 s[42:43], s48, v18
	s_and_b64 s[40:41], s[40:41], s[34:35]
	s_and_b64 s[42:43], s[42:43], s[38:39]
	s_or_b64 s[40:41], s[40:41], s[30:31]
	s_or_b64 s[42:43], s[42:43], s[44:45]
	s_or_b64 s[40:41], s[40:41], s[26:27]
	s_or_b64 s[42:43], s[42:43], s[28:29]
	v_mov_b32_e32 v44, s40
	v_mov_b32_e32 v45, s41
	v_mov_b32_e32 v46, s42
	v_mov_b32_e32 v47, s43
	v_cmp_lt_u32_e64 s[30:31], s18, v4
	v_cmp_lt_u32_e64 s[44:45], s18, v12
	v_cmp_eq_u32_e64 s[34:35], s18, v4
	v_cmp_eq_u32_e64 s[38:39], s18, v12
	s_bcnt1_i32_b64 s48, s[30:31]
	s_bcnt1_i32_b64 s49, s[44:45]
	s_add_i32 s48, s48, s49
	s_sub_i32 s48, 15, s48
	s_and_b64 s[34:35], s[34:35], s[22:23]
	s_and_b64 s[38:39], s[38:39], s[24:25]
	s_bcnt1_i32_b64 s49, s[34:35]
	v_and_b32_e32 v17, s34, v116
	v_and_b32_e32 v18, s35, v115
	v_bcnt_u32_b32 v17, v17, 0
	v_bcnt_u32_b32 v17, v18, v17
	v_and_b32_e32 v18, s38, v116
	v_and_b32_e32 v19, s39, v115
	v_bcnt_u32_b32 v18, v18, s49
	v_bcnt_u32_b32 v18, v19, v18
	v_cmp_gt_i32_e64 s[40:41], s48, v17
	v_cmp_gt_i32_e64 s[42:43], s48, v18
	s_and_b64 s[40:41], s[40:41], s[34:35]
	s_and_b64 s[42:43], s[42:43], s[38:39]
	s_or_b64 s[40:41], s[40:41], s[30:31]
	s_or_b64 s[42:43], s[42:43], s[44:45]
	s_or_b64 s[40:41], s[40:41], s[26:27]
	s_or_b64 s[42:43], s[42:43], s[28:29]
	v_mov_b32_e32 v48, s40
	v_mov_b32_e32 v49, s41
	v_mov_b32_e32 v50, s42
	v_mov_b32_e32 v51, s43
	v_cmp_lt_u32_e64 s[30:31], s19, v5
	v_cmp_lt_u32_e64 s[44:45], s19, v13
	v_cmp_eq_u32_e64 s[34:35], s19, v5
	v_cmp_eq_u32_e64 s[38:39], s19, v13
	s_bcnt1_i32_b64 s48, s[30:31]
	s_bcnt1_i32_b64 s49, s[44:45]
	s_add_i32 s48, s48, s49
	s_sub_i32 s48, 15, s48
	s_and_b64 s[34:35], s[34:35], s[22:23]
	s_and_b64 s[38:39], s[38:39], s[24:25]
	s_bcnt1_i32_b64 s49, s[34:35]
	v_and_b32_e32 v17, s34, v116
	v_and_b32_e32 v18, s35, v115
	v_bcnt_u32_b32 v17, v17, 0
	v_bcnt_u32_b32 v17, v18, v17
	v_and_b32_e32 v18, s38, v116
	v_and_b32_e32 v19, s39, v115
	v_bcnt_u32_b32 v18, v18, s49
	v_bcnt_u32_b32 v18, v19, v18
	v_cmp_gt_i32_e64 s[40:41], s48, v17
	v_cmp_gt_i32_e64 s[42:43], s48, v18
	s_and_b64 s[40:41], s[40:41], s[34:35]
	s_and_b64 s[42:43], s[42:43], s[38:39]
	s_or_b64 s[40:41], s[40:41], s[30:31]
	s_or_b64 s[42:43], s[42:43], s[44:45]
	s_or_b64 s[40:41], s[40:41], s[26:27]
	s_or_b64 s[42:43], s[42:43], s[28:29]
	v_mov_b32_e32 v52, s40
	v_mov_b32_e32 v53, s41
	v_mov_b32_e32 v54, s42
	v_mov_b32_e32 v55, s43
	v_cmp_lt_u32_e64 s[30:31], s20, v6
	v_cmp_lt_u32_e64 s[44:45], s20, v14
	v_cmp_eq_u32_e64 s[34:35], s20, v6
	v_cmp_eq_u32_e64 s[38:39], s20, v14
	s_bcnt1_i32_b64 s48, s[30:31]
	s_bcnt1_i32_b64 s49, s[44:45]
	s_add_i32 s48, s48, s49
	s_sub_i32 s48, 15, s48
	s_and_b64 s[34:35], s[34:35], s[22:23]
	s_and_b64 s[38:39], s[38:39], s[24:25]
	s_bcnt1_i32_b64 s49, s[34:35]
	v_and_b32_e32 v17, s34, v116
	v_and_b32_e32 v18, s35, v115
	v_bcnt_u32_b32 v17, v17, 0
	v_bcnt_u32_b32 v17, v18, v17
	v_and_b32_e32 v18, s38, v116
	v_and_b32_e32 v19, s39, v115
	v_bcnt_u32_b32 v18, v18, s49
	v_bcnt_u32_b32 v18, v19, v18
	v_cmp_gt_i32_e64 s[40:41], s48, v17
	v_cmp_gt_i32_e64 s[42:43], s48, v18
	s_and_b64 s[40:41], s[40:41], s[34:35]
	s_and_b64 s[42:43], s[42:43], s[38:39]
	s_or_b64 s[40:41], s[40:41], s[30:31]
	s_or_b64 s[42:43], s[42:43], s[44:45]
	s_or_b64 s[40:41], s[40:41], s[26:27]
	s_or_b64 s[42:43], s[42:43], s[28:29]
	v_mov_b32_e32 v56, s40
	v_mov_b32_e32 v57, s41
	v_mov_b32_e32 v58, s42
	v_mov_b32_e32 v59, s43
	v_cmp_lt_u32_e64 s[30:31], s21, v7
	v_cmp_lt_u32_e64 s[44:45], s21, v15
	v_cmp_eq_u32_e64 s[34:35], s21, v7
	v_cmp_eq_u32_e64 s[38:39], s21, v15
	s_bcnt1_i32_b64 s48, s[30:31]
	s_bcnt1_i32_b64 s49, s[44:45]
	s_add_i32 s48, s48, s49
	s_sub_i32 s48, 15, s48
	s_and_b64 s[34:35], s[34:35], s[22:23]
	s_and_b64 s[38:39], s[38:39], s[24:25]
	s_bcnt1_i32_b64 s49, s[34:35]
	v_and_b32_e32 v17, s34, v116
	v_and_b32_e32 v18, s35, v115
	v_bcnt_u32_b32 v17, v17, 0
	v_bcnt_u32_b32 v17, v18, v17
	v_and_b32_e32 v18, s38, v116
	v_and_b32_e32 v19, s39, v115
	v_bcnt_u32_b32 v18, v18, s49
	v_bcnt_u32_b32 v18, v19, v18
	v_cmp_gt_i32_e64 s[40:41], s48, v17
	v_cmp_gt_i32_e64 s[42:43], s48, v18
	s_and_b64 s[40:41], s[40:41], s[34:35]
	s_and_b64 s[42:43], s[42:43], s[38:39]
	s_or_b64 s[40:41], s[40:41], s[30:31]
	s_or_b64 s[42:43], s[42:43], s[44:45]
	s_or_b64 s[40:41], s[40:41], s[26:27]
	s_or_b64 s[42:43], s[42:43], s[28:29]
	v_mov_b32_e32 v60, s40
	v_mov_b32_e32 v61, s41
	v_mov_b32_e32 v62, s42
	v_mov_b32_e32 v63, s43
	v_readlane_b32 s49, v254, 35
	s_nop 0
	s_add_i32 s49, s49, 0x18400
	v_mov_b32_e32 v20, s49
	s_and_saveexec_b64 s[10:11], s[12:13]
	ds_write_b128 v20, v[32:35] offset:0
	ds_write_b128 v20, v[36:39] offset:16
	ds_write_b128 v20, v[40:43] offset:32
	ds_write_b128 v20, v[44:47] offset:48
	ds_write_b128 v20, v[48:51] offset:64
	ds_write_b128 v20, v[52:55] offset:80
	ds_write_b128 v20, v[56:59] offset:96
	ds_write_b128 v20, v[60:63] offset:112
	s_or_b64 exec, exec, s[10:11]
